# attention QK^T section: all fragment reads issued up front into free VGPRs, MFMAs behind counted lgkmcnt waits
# baseline (speedup 1.0000x reference)
; #define LAS __attribute__((address_space(3)))
; #define MFMA16(a, b, c) __builtin_amdgcn_mfma_f32_16x16x32_bf16((a), (b), (c), 0, 0, 0)
; __device__ __forceinline__ void attn_item(const Args& a, LAS unsigned char* lds, int item, int tid, int wave, int lane) {
;     ...
;         const int rt = 2 * (wave & 1) + rr;
;         const bf16x8 bq0 = *(const LAS bf16x8*)(QS + (g * 64 + 16 * rt + fr) * LP + 8 * fq), bq1 = *(const LAS bf16x8*)(QS + (g * 64 + 16 * rt + fr) * LP + 32 + 8 * fq);
;         f32x4 s[9];
; #pragma unroll
;         for (int t = 0; t < 9; ++t) {
;             const LAS bf16_t* kp = KS + (16 * (rt + t) + fr) * LP + 8 * fq;
;             const bf16x8 k0 = *(const LAS bf16x8*)kp, k1 = *(const LAS bf16x8*)(kp + 32);
;             f32x4 v = (f32x4){0.f, 0.f, 0.f, 0.f};
;             v = MFMA16(k0, bq0, v); v = MFMA16(k1, bq1, v); s[t] = v;
;         }
.LBB0_1103:
	s_or_b32 s45, s45, s38
	s_add_i32 s52, s45, 16
	s_add_i32 s51, s45, 32
	s_add_i32 s50, s45, 48
	s_or_b32 s49, s45, 64
	s_add_i32 s48, s45, 0x50
	s_add_i32 s47, s45, 0x60
	s_add_i32 s46, s45, 0x70
	v_or_b32_e32 v0, s45, v100
	v_mad_u32_u24 v0, v0, s1, v84
	v_or_b32_e32 v1, s45, v92
	v_mad_u32_u24 v3, v1, s1, v84
	ds_read_b128 v[32:35], v0 offset:53248
	ds_read_b128 v[44:47], v0 offset:53312
	ds_read_b128 v[160:163], v3
	ds_read_b128 v[164:167], v3 offset:64
	v_or_b32_e32 v1, s52, v92
	v_mad_u32_u24 v1, v1, s1, v84
	ds_read_b128 v[168:171], v1
	ds_read_b128 v[172:175], v1 offset:64
	v_or_b32_e32 v1, s51, v92
	v_mad_u32_u24 v1, v1, s1, v84
	ds_read_b128 v[176:179], v1
	ds_read_b128 v[180:183], v1 offset:64
	v_or_b32_e32 v1, s50, v92
	v_mad_u32_u24 v1, v1, s1, v84
	ds_read_b128 v[184:187], v1
	ds_read_b128 v[188:191], v1 offset:64
	v_or_b32_e32 v1, s49, v92
	v_mad_u32_u24 v1, v1, s1, v84
	ds_read_b128 v[192:195], v1
	ds_read_b128 v[196:199], v1 offset:64
	v_or_b32_e32 v1, s48, v92
	v_mad_u32_u24 v1, v1, s1, v84
	ds_read_b128 v[200:203], v1
	ds_read_b128 v[204:207], v1 offset:64
	s_andn2_b64 vcc, exec, s[34:35]
	s_waitcnt lgkmcnt(10)
	v_mfma_f32_16x16x32_bf16 v[36:39], v[160:163], v[32:35], 0
	v_mfma_f32_16x16x32_bf16 v[36:39], v[164:167], v[44:47], v[36:39]
	v_or_b32_e32 v1, s47, v92
	v_mad_u32_u24 v1, v1, s1, v84
	ds_read_b128 v[208:211], v1
	ds_read_b128 v[212:215], v1 offset:64
	s_waitcnt lgkmcnt(10)
	v_mfma_f32_16x16x32_bf16 v[28:31], v[168:171], v[32:35], 0
	v_mfma_f32_16x16x32_bf16 v[28:31], v[172:175], v[44:47], v[28:31]
	v_or_b32_e32 v1, s46, v92
	v_mad_u32_u24 v1, v1, s1, v84
	ds_read_b128 v[216:219], v1
	ds_read_b128 v[220:223], v1 offset:64
	s_waitcnt lgkmcnt(10)
	v_mfma_f32_16x16x32_bf16 v[24:27], v[176:179], v[32:35], 0
	v_mfma_f32_16x16x32_bf16 v[24:27], v[180:183], v[44:47], v[24:27]
	ds_read_b128 v[224:227], v3 offset:18432
	ds_read_b128 v[228:231], v3 offset:18496
	s_waitcnt lgkmcnt(10)
	v_mfma_f32_16x16x32_bf16 v[20:23], v[184:187], v[32:35], 0
	v_mfma_f32_16x16x32_bf16 v[20:23], v[188:191], v[44:47], v[20:23]
	s_waitcnt lgkmcnt(8)
	v_mfma_f32_16x16x32_bf16 v[16:19], v[192:195], v[32:35], 0
	v_mfma_f32_16x16x32_bf16 v[16:19], v[196:199], v[44:47], v[16:19]
	s_waitcnt lgkmcnt(6)
	v_mfma_f32_16x16x32_bf16 v[12:15], v[200:203], v[32:35], 0
	v_mfma_f32_16x16x32_bf16 v[12:15], v[204:207], v[44:47], v[12:15]
	s_waitcnt lgkmcnt(4)
	v_mfma_f32_16x16x32_bf16 v[8:11], v[208:211], v[32:35], 0
	v_mfma_f32_16x16x32_bf16 v[8:11], v[212:215], v[44:47], v[8:11]
	s_waitcnt lgkmcnt(2)
	v_mfma_f32_16x16x32_bf16 v[4:7], v[216:219], v[32:35], 0
	v_mfma_f32_16x16x32_bf16 v[4:7], v[220:223], v[44:47], v[4:7]
	s_waitcnt lgkmcnt(0)
	v_mfma_f32_16x16x32_bf16 v[32:35], v[224:227], v[32:35], 0
	v_mfma_f32_16x16x32_bf16 v[32:35], v[228:231], v[44:47], v[32:35]
	s_cbranch_vccz .LBB0_1101
	v_mov_b32_e32 v0, s41
	v_cndmask_b32_e64 v0, v0, v36, s[12:13]
	v_cndmask_b32_e64 v36, v37, v108, s[14:15]
	v_cndmask_b32_e64 v3, v108, v38, s[16:17]
	v_cndmask_b32_e64 v1, v108, v39, s[18:19]
	s_branch .LBB0_1102
